# speedup vs baseline: 1.0075x; 1.0019x over previous
; __device__ __forceinline__ f32x4 mfma16(bf16x8 a, bf16x8 b, f32x4 c) { return __builtin_amdgcn_mfma_f32_16x16x32_bf16(a, b, c, 0, 0, 0); }
; __device__ void phase_na(const Params& P, unsigned char* smem) {
;     ...
;     for (int uu = ((int)blockIdx.x >> 3) * 8 + wid; uu < 2048; uu += nbh * 8) {
;         const int grow = uu >> 2, j = uu & 3;
;         int rows, r, tokbase;
;         if (grow < 256) { rows = 256; r = grow; tokbase = 0; } else { const int s = (grow - 256) >> 6; r = (grow - 256) & 63; rows = 64; tokbase = TP + s * 4096; }
;         const int rs = min(max(r - 4, 0), rows - 8);
;         const int q0 = j * 16, k0 = min(max(q0 - 8, 0), 32);
;         const size_t qtok = (size_t)tokbase + r * 64 + q0 + l15;
;         const bf16_t* qptr = Qp + qtok * 1024 + h * 128 + l4 * 8;
;         bf16x8 qf[4];
; #pragma unroll
;         for (int ks = 0; ks < 4; ++ks) qf[ks] = *(const bf16x8*)(qptr + ks * 32);
;         f32x4 st[8][2];
; #pragma unroll
;         for (int i = 0; i < 8; ++i)
; #pragma unroll
;             for (int a = 0; a < 2; ++a) {
;                 const size_t ktok = (size_t)tokbase + (rs + i) * 64 + k0 + (l15 >> 2) * 8 + a * 4 + (l15 & 3);
;                 const bf16_t* kptr = Kp + ktok * 1024 + h * 128 + l4 * 8;
;                 f32x4 c = {0.f, 0.f, 0.f, 0.f};
; #pragma unroll
;                 for (int ks = 0; ks < 4; ++ks) c = mfma16(*(const bf16x8*)(kptr + ks * 32), qf[ks], c);
;                 st[i][a] = c;
;             }
.LBB0_210:
	v_ashrrev_i32_e32 v0, 2, v84
	v_and_b32_e32 v1, 63, v0
	v_cmp_gt_i32_e32 vcc, s42, v0
	v_lshlrev_b32_e32 v2, 6, v0
	v_and_b32_e32 v2, 0xfffff000, v2
	v_cndmask_b32_e32 v136, v1, v0, vcc
	v_max_i32_e32 v0, 4, v136
	v_and_b32_e32 v137, 48, v88
	v_cndmask_b32_e64 v70, v2, 0, vcc
	v_add_u32_e32 v4, -4, v0
	v_sub_u32_e64 v5, v137, 8 clamp
	v_cndmask_b32_e32 v6, 56, v89, vcc
	v_min_u32_e32 v138, v4, v6
	v_min_u32_e32 v67, 32, v5
	v_or_b32_e32 v4, v70, v85
	v_add_u32_e32 v4, v4, v67
	v_mov_b32_e32 v5, v71
	v_lshlrev_b32_e32 v82, 6, v138
	v_mov_b32_e32 v83, v71
	v_lshlrev_b32_e32 v0, 6, v136
	v_lshl_add_u64 v[6:7], v[82:83], 0, v[4:5]
	v_ashrrev_i32_e32 v1, 31, v0
	v_lshlrev_b64 v[6:7], 11, v[6:7]
	v_lshl_add_u64 v[80:81], v[70:71], 0, v[0:1]
	v_lshl_add_u64 v[60:61], v[74:75], 0, v[6:7]
	v_or_b32_e32 v0, v80, v137
	global_load_dwordx4 v[6:9], v[60:61], off
	v_add_u32_e32 v14, 64, v82
	v_mov_b32_e32 v15, v71
	v_or_b32_e32 v80, v0, v64
	v_lshl_add_u64 v[14:15], v[14:15], 0, v[4:5]
	v_lshlrev_b64 v[0:1], 11, v[80:81]
	v_add_co_u32_e32 v62, vcc, s43, v60
	v_lshlrev_b64 v[14:15], 11, v[14:15]
	v_mov_b32_e32 v19, v71
	v_add_u32_e32 v18, 0x80, v82
	v_lshl_add_u64 v[58:59], v[72:73], 0, v[0:1]
	v_addc_co_u32_e32 v63, vcc, 0, v61, vcc
	v_lshl_add_u64 v[90:91], v[74:75], 0, v[14:15]
	v_lshl_add_u64 v[18:19], v[18:19], 0, v[4:5]
	global_load_dwordx4 v[0:3], v[58:59], off
	v_lshlrev_b64 v[18:19], 11, v[18:19]
	v_add_co_u32_e32 v98, vcc, s43, v90
	v_lshl_add_u64 v[96:97], v[74:75], 0, v[18:19]
	s_nop 0
	v_addc_co_u32_e32 v99, vcc, 0, v91, vcc
	v_add_co_u32_e32 v100, vcc, s43, v96
	global_load_dwordx4 v[10:13], v[62:63], off
	s_nop 0
	v_addc_co_u32_e32 v101, vcc, 0, v97, vcc
	global_load_dwordx4 v[14:17], v[90:91], off
	global_load_dwordx4 v[18:21], v[96:97], off
	global_load_dwordx4 v[22:25], v[98:99], off
	global_load_dwordx4 v[26:29], v[100:101], off
	global_load_dwordx4 v[30:33], v[60:61], off offset:64
	global_load_dwordx4 v[92:95], v[58:59], off offset:64
	global_load_dwordx4 v[34:37], v[62:63], off offset:64
	global_load_dwordx4 v[38:41], v[90:91], off offset:64
	global_load_dwordx4 v[42:45], v[96:97], off offset:64
	global_load_dwordx4 v[46:49], v[98:99], off offset:64
	global_load_dwordx4 v[50:53], v[100:101], off offset:64
	global_load_dwordx4 v[54:57], v[60:61], off offset:128
	global_load_dwordx4 v[104:107], v[58:59], off offset:128
	s_waitcnt vmcnt(14)
	v_mfma_f32_16x16x32_bf16 v[6:9], v[6:9], v[0:3], 0
	s_waitcnt vmcnt(7)
	v_mfma_f32_16x16x32_bf16 v[6:9], v[30:33], v[92:95], v[6:9]
	global_load_dwordx4 v[30:33], v[62:63], off offset:128
	v_mfma_f32_16x16x32_bf16 v[10:13], v[10:13], v[0:3], 0
	s_waitcnt vmcnt(7)
	v_mfma_f32_16x16x32_bf16 v[10:13], v[34:37], v[92:95], v[10:13]
	global_load_dwordx4 v[34:37], v[90:91], off offset:128
	v_mfma_f32_16x16x32_bf16 v[14:17], v[14:17], v[0:3], 0
	v_mfma_f32_16x16x32_bf16 v[18:21], v[18:21], v[0:3], 0
	v_mfma_f32_16x16x32_bf16 v[22:25], v[22:25], v[0:3], 0
	v_mfma_f32_16x16x32_bf16 v[26:29], v[26:29], v[0:3], 0
	s_waitcnt vmcnt(7)
	v_mfma_f32_16x16x32_bf16 v[14:17], v[38:41], v[92:95], v[14:17]
	global_load_dwordx4 v[38:41], v[96:97], off offset:128
	s_waitcnt vmcnt(7)
	v_mfma_f32_16x16x32_bf16 v[18:21], v[42:45], v[92:95], v[18:21]
	global_load_dwordx4 v[42:45], v[98:99], off offset:128
	s_waitcnt vmcnt(7)
	v_mfma_f32_16x16x32_bf16 v[22:25], v[46:49], v[92:95], v[22:25]
	global_load_dwordx4 v[46:49], v[100:101], off offset:128
	s_waitcnt vmcnt(7)
	v_mfma_f32_16x16x32_bf16 v[26:29], v[50:53], v[92:95], v[26:29]
	global_load_dwordx4 v[50:53], v[60:61], off offset:192
	global_load_dwordx4 v[108:111], v[58:59], off offset:192
	s_waitcnt vmcnt(7)
	v_mfma_f32_16x16x32_bf16 v[6:9], v[54:57], v[104:107], v[6:9]
	global_load_dwordx4 v[54:57], v[62:63], off offset:192
	s_waitcnt vmcnt(7)
	v_mfma_f32_16x16x32_bf16 v[10:13], v[30:33], v[104:107], v[10:13]
	global_load_dwordx4 v[30:33], v[90:91], off offset:192
	s_waitcnt vmcnt(7)
	v_mfma_f32_16x16x32_bf16 v[14:17], v[34:37], v[104:107], v[14:17]
	global_load_dwordx4 v[34:37], v[96:97], off offset:192
	s_waitcnt vmcnt(3)
	v_mfma_f32_16x16x32_bf16 v[60:63], v[50:53], v[108:111], v[6:9]
	s_nop 2
	v_mov_b32_e32 v7, v71
	v_add_u32_e32 v6, 0xc0, v82
	v_lshl_add_u64 v[6:7], v[6:7], 0, v[4:5]
	v_lshlrev_b64 v[6:7], 11, v[6:7]
	s_waitcnt vmcnt(2)
	v_mfma_f32_16x16x32_bf16 v[56:59], v[54:57], v[108:111], v[10:13]
	s_waitcnt vmcnt(1)
	v_mfma_f32_16x16x32_bf16 v[52:55], v[30:33], v[108:111], v[14:17]
	v_lshl_add_u64 v[30:31], v[74:75], 0, v[6:7]
	global_load_dwordx4 v[6:9], v[30:31], off
	global_load_dwordx4 v[10:13], v[30:31], off offset:64
	v_mfma_f32_16x16x32_bf16 v[18:21], v[38:41], v[104:107], v[18:21]
	global_load_dwordx4 v[38:41], v[98:99], off offset:192
	global_load_dwordx4 v[14:17], v[30:31], off offset:128
	v_mfma_f32_16x16x32_bf16 v[22:25], v[42:45], v[104:107], v[22:25]
	global_load_dwordx4 v[96:99], v[100:101], off offset:192
	v_mfma_f32_16x16x32_bf16 v[26:29], v[46:49], v[104:107], v[26:29]
	s_waitcnt vmcnt(5)
	v_mfma_f32_16x16x32_bf16 v[44:47], v[34:37], v[108:111], v[18:21]
	s_nop 2
	global_load_dwordx4 v[18:21], v[30:31], off offset:192
	s_waitcnt vmcnt(3)
	v_mfma_f32_16x16x32_bf16 v[48:51], v[38:41], v[108:111], v[22:25]
	s_nop 2
	v_add_co_u32_e32 v22, vcc, s43, v30
	v_mfma_f32_16x16x32_bf16 v[6:9], v[6:9], v[0:3], 0
	s_nop 0
	v_addc_co_u32_e32 v23, vcc, 0, v31, vcc
	v_mfma_f32_16x16x32_bf16 v[6:9], v[10:13], v[92:95], v[6:9]
	global_load_dwordx4 v[10:13], v[22:23], off
	s_waitcnt vmcnt(3)
	v_mfma_f32_16x16x32_bf16 v[6:9], v[14:17], v[104:107], v[6:9]
	global_load_dwordx4 v[14:17], v[22:23], off offset:64
	s_waitcnt vmcnt(2)
; __device__ __forceinline__ f32x4 mfma16(bf16x8 a, bf16x8 b, f32x4 c) { return __builtin_amdgcn_mfma_f32_16x16x32_bf16(a, b, c, 0, 0, 0); }
; __device__ void phase_na(const Params& P, unsigned char* smem) {
;     ...
;                 const size_t ktok = (size_t)tokbase + (rs + i) * 64 + k0 + (l15 >> 2) * 8 + a * 4 + (l15 & 3);
;                 const bf16_t* kptr = Kp + ktok * 1024 + h * 128 + l4 * 8;
;                 f32x4 c = {0.f, 0.f, 0.f, 0.f};
; #pragma unroll
;                 for (int ks = 0; ks < 4; ++ks) c = mfma16(*(const bf16x8*)(kptr + ks * 32), qf[ks], c);
;                 st[i][a] = c;
;             }
;         const int qc = q0 + l15, cs = min(max(qc - 8, 0), 48);
;         float mx = -1e30f;
; #pragma unroll
;         for (int i = 0; i < 8; ++i) {
;             const float* brow = rpb_s + (h * 15 + (rs + i - r + 7)) * 31;
; #pragma unroll
;             for (int a = 0; a < 2; ++a)
; #pragma unroll
;                 for (int jj = 0; jj < 4; ++jj) {
;                     const int kc = k0 + l4 * 8 + a * 4 + jj;
;                     const bool valid = (kc >= cs) && (kc < cs + 16);
;                     const int dc = min(max(kc - qc, -15), 15) + 15;
	v_mfma_f32_16x16x32_bf16 v[36:39], v[18:21], v[108:111], v[6:9]
	global_load_dwordx4 v[18:21], v[22:23], off offset:192
	s_nop 3
	global_load_dwordx4 v[6:9], v[22:23], off offset:128
	v_mfma_f32_16x16x32_bf16 v[40:43], v[96:99], v[108:111], v[26:29]
	s_waitcnt vmcnt(3)
	v_mfma_f32_16x16x32_bf16 v[10:13], v[10:13], v[0:3], 0
	s_waitcnt vmcnt(2)
	v_mfma_f32_16x16x32_bf16 v[10:13], v[14:17], v[92:95], v[10:13]
	v_add_u32_e32 v14, 0x100, v82
	v_mov_b32_e32 v15, v71
	v_lshl_add_u64 v[14:15], v[14:15], 0, v[4:5]
	v_lshlrev_b64 v[14:15], 11, v[14:15]
	v_lshl_add_u64 v[22:23], v[74:75], 0, v[14:15]
	global_load_dwordx4 v[14:17], v[22:23], off
	s_waitcnt vmcnt(1)
	v_mfma_f32_16x16x32_bf16 v[6:9], v[6:9], v[104:107], v[10:13]
	s_nop 2
	global_load_dwordx4 v[10:13], v[22:23], off offset:64
	v_mfma_f32_16x16x32_bf16 v[32:35], v[18:21], v[108:111], v[6:9]
	global_load_dwordx4 v[18:21], v[22:23], off offset:192
	s_nop 1
	global_load_dwordx4 v[6:9], v[22:23], off offset:128
	v_add_co_u32_e32 v22, vcc, s43, v22
	s_waitcnt vmcnt(3)
	v_mfma_f32_16x16x32_bf16 v[14:17], v[14:17], v[0:3], 0
	v_addc_co_u32_e32 v23, vcc, 0, v23, vcc
	s_waitcnt vmcnt(2)
	v_mfma_f32_16x16x32_bf16 v[10:13], v[10:13], v[92:95], v[14:17]
	s_nop 4
	global_load_dwordx4 v[14:17], v[22:23], off
	s_waitcnt vmcnt(1)
	v_mfma_f32_16x16x32_bf16 v[6:9], v[6:9], v[104:107], v[10:13]
	s_nop 2
	global_load_dwordx4 v[10:13], v[22:23], off offset:64
	v_mfma_f32_16x16x32_bf16 v[28:31], v[18:21], v[108:111], v[6:9]
	global_load_dwordx4 v[18:21], v[22:23], off offset:192
	s_nop 1
	global_load_dwordx4 v[6:9], v[22:23], off offset:128
	s_waitcnt vmcnt(3)
	v_mfma_f32_16x16x32_bf16 v[14:17], v[14:17], v[0:3], 0
	s_waitcnt vmcnt(2)
	v_mfma_f32_16x16x32_bf16 v[10:13], v[10:13], v[92:95], v[14:17]
	s_nop 5
	v_add_u32_e32 v14, 0x140, v82
	v_mov_b32_e32 v15, v71
	v_lshl_add_u64 v[14:15], v[14:15], 0, v[4:5]
	v_lshlrev_b64 v[14:15], 11, v[14:15]
	v_lshl_add_u64 v[22:23], v[74:75], 0, v[14:15]
	global_load_dwordx4 v[14:17], v[22:23], off
	s_waitcnt vmcnt(1)
	v_mfma_f32_16x16x32_bf16 v[6:9], v[6:9], v[104:107], v[10:13]
	v_add_co_u32_e32 v90, vcc, s43, v22
	s_nop 1
	global_load_dwordx4 v[10:13], v[22:23], off offset:64
	v_mfma_f32_16x16x32_bf16 v[24:27], v[18:21], v[108:111], v[6:9]
	global_load_dwordx4 v[18:21], v[22:23], off offset:192
	v_addc_co_u32_e32 v91, vcc, 0, v23, vcc
	s_nop 0
	global_load_dwordx4 v[6:9], v[22:23], off offset:128
	s_waitcnt vmcnt(3)
	v_mfma_f32_16x16x32_bf16 v[14:17], v[14:17], v[0:3], 0
	global_load_dwordx4 v[96:99], v[90:91], off offset:192
	s_waitcnt vmcnt(3)
	v_mfma_f32_16x16x32_bf16 v[10:13], v[10:13], v[92:95], v[14:17]
	s_nop 4
	global_load_dwordx4 v[14:17], v[90:91], off
	s_waitcnt vmcnt(2)
	v_mfma_f32_16x16x32_bf16 v[6:9], v[6:9], v[104:107], v[10:13]
	s_nop 2
	global_load_dwordx4 v[10:13], v[90:91], off offset:64
	v_mfma_f32_16x16x32_bf16 v[20:23], v[18:21], v[108:111], v[6:9]
	s_nop 2
	global_load_dwordx4 v[6:9], v[90:91], off offset:128
	s_waitcnt vmcnt(2)
	v_mfma_f32_16x16x32_bf16 v[14:17], v[14:17], v[0:3], 0
	s_waitcnt vmcnt(1)
	v_mfma_f32_16x16x32_bf16 v[10:13], v[10:13], v[92:95], v[14:17]
	s_nop 5
	v_add_u32_e32 v14, 0x180, v82
	v_mov_b32_e32 v15, v71
	v_lshl_add_u64 v[14:15], v[14:15], 0, v[4:5]
	v_lshlrev_b64 v[14:15], 11, v[14:15]
	v_lshl_add_u64 v[14:15], v[74:75], 0, v[14:15]
	global_load_dwordx4 v[100:103], v[14:15], off
	s_waitcnt vmcnt(1)
	v_mfma_f32_16x16x32_bf16 v[6:9], v[6:9], v[104:107], v[10:13]
	v_add_co_u32_e32 v90, vcc, s43, v14
	s_nop 1
	global_load_dwordx4 v[10:13], v[14:15], off offset:64
	v_mfma_f32_16x16x32_bf16 v[16:19], v[96:99], v[108:111], v[6:9]
	v_addc_co_u32_e32 v91, vcc, 0, v15, vcc
	global_load_dwordx4 v[112:115], v[90:91], off offset:64
	s_nop 0
	global_load_dwordx4 v[6:9], v[14:15], off offset:128
	s_waitcnt vmcnt(3)
	v_mfma_f32_16x16x32_bf16 v[96:99], v[100:103], v[0:3], 0
	global_load_dwordx4 v[100:103], v[14:15], off offset:192
	s_waitcnt vmcnt(3)
	v_mfma_f32_16x16x32_bf16 v[10:13], v[10:13], v[92:95], v[96:99]
	s_nop 4
	global_load_dwordx4 v[96:99], v[90:91], off
	s_waitcnt vmcnt(2)
	v_mfma_f32_16x16x32_bf16 v[6:9], v[6:9], v[104:107], v[10:13]
	s_nop 2
	v_add_u32_e32 v10, 0x1c0, v82
	v_mov_b32_e32 v11, v71
	v_lshl_add_u64 v[4:5], v[10:11], 0, v[4:5]
	v_lshlrev_b64 v[4:5], 11, v[4:5]
	v_lshl_add_u64 v[10:11], v[74:75], 0, v[4:5]
	s_waitcnt vmcnt(1)
	v_mfma_f32_16x16x32_bf16 v[12:15], v[100:103], v[108:111], v[6:9]
	s_nop 2
	global_load_dwordx4 v[6:9], v[90:91], off offset:128
	global_load_dwordx4 v[100:103], v[90:91], off offset:192
	global_load_dwordx4 v[116:119], v[10:11], off
	v_add_co_u32_e32 v90, vcc, s43, v10
	s_waitcnt vmcnt(3)
	v_mfma_f32_16x16x32_bf16 v[96:99], v[96:99], v[0:3], 0
	v_addc_co_u32_e32 v91, vcc, 0, v11, vcc
	v_mfma_f32_16x16x32_bf16 v[96:99], v[112:115], v[92:95], v[96:99]
	global_load_dwordx4 v[112:115], v[10:11], off offset:64
	global_load_dwordx4 v[120:123], v[10:11], off offset:128
	global_load_dwordx4 v[124:127], v[10:11], off offset:192
	global_load_dwordx4 v[128:131], v[90:91], off
	s_waitcnt vmcnt(6)
	v_mfma_f32_16x16x32_bf16 v[4:7], v[6:9], v[104:107], v[96:99]
	global_load_dwordx4 v[132:135], v[90:91], off offset:64
	s_nop 1
	v_or_b32_e32 v99, v137, v64
	v_max_i32_e32 v83, 8, v99
	s_waitcnt vmcnt(6)
	v_mfma_f32_16x16x32_bf16 v[8:11], v[100:103], v[108:111], v[4:7]
	v_add_u32_e32 v83, -8, v83
	v_min_u32_e32 v100, 48, v83
	v_sub_u32_e32 v83, s25, v136
	s_waitcnt vmcnt(5)
	v_mfma_f32_16x16x32_bf16 v[4:7], v[116:119], v[0:3], 0
	global_load_dwordx4 v[116:119], v[90:91], off offset:128
	v_add_u32_e32 v83, v83, v138
	v_add_u32_e32 v101, v67, v68
	s_waitcnt vmcnt(5)
; __device__ void phase_na(const Params& P, unsigned char* smem) {
;     ...
;         for (int i = 0; i < 8; ++i) {
;             const float* brow = rpb_s + (h * 15 + (rs + i - r + 7)) * 31;
; #pragma unroll
;             for (int a = 0; a < 2; ++a)
; #pragma unroll
;                 for (int jj = 0; jj < 4; ++jj) {
;                     const int kc = k0 + l4 * 8 + a * 4 + jj;
;                     const bool valid = (kc >= cs) && (kc < cs + 16);
;                     const int dc = min(max(kc - qc, -15), 15) + 15;
;                     const float s = valid ? st[i][a][jj] * scale + brow[dc] : -1e30f;
;                     st[i][a][jj] = s; mx = fmaxf(mx, s);
;                 }
	v_mfma_f32_16x16x32_bf16 v[4:7], v[112:115], v[92:95], v[4:7]
	global_load_dwordx4 v[112:115], v[90:91], off offset:192
	v_add_u32_e32 v102, 16, v100
	v_mul_lo_u32 v83, v83, s44
	s_waitcnt vmcnt(3)
	v_mfma_f32_16x16x32_bf16 v[0:3], v[128:131], v[0:3], 0
	v_cmp_ge_u32_e32 vcc, v101, v100
	v_cmp_lt_u32_e64 s[0:1], v101, v102
	v_sub_u32_e32 v90, v101, v99
	s_waitcnt vmcnt(2)
	v_mfma_f32_16x16x32_bf16 v[0:3], v[132:135], v[92:95], v[0:3]
	v_add_u32_e32 v91, 0, v83
	s_and_b64 s[8:9], vcc, s[0:1]
	v_mov_b32_e32 v83, 0xf149f2ca
	v_mfma_f32_16x16x32_bf16 v[4:7], v[120:123], v[104:107], v[4:7]
	v_med3_i32 v92, v90, -15, 15
	v_mov_b32_e32 v90, 0xf149f2ca
	s_waitcnt vmcnt(1)
	v_mfma_f32_16x16x32_bf16 v[0:3], v[116:119], v[104:107], v[0:3]
	v_mfma_f32_16x16x32_bf16 v[4:7], v[124:127], v[108:111], v[4:7]
	s_waitcnt vmcnt(0)
	v_mfma_f32_16x16x32_bf16 v[0:3], v[112:115], v[108:111], v[0:3]
	v_lshl_add_u32 v253, v92, 2, v91
	ds_read_b32 v242, v253 offset:60
	v_lshl_add_u32 v253, v92, 2, v91
	ds_read_b32 v251, v253 offset:184
	s_waitcnt lgkmcnt(1)
	v_fmac_f32_e32 v242, 0x3db504f3, v60
	v_cndmask_b32_e64 v90, v90, v242, s[8:9]
	v_or_b32_e32 v60, 1, v101
	v_cmp_ge_u32_e32 vcc, v60, v100
	v_cmp_lt_u32_e64 s[0:1], v60, v102
	v_sub_u32_e32 v60, v60, v99
	s_and_b64 s[10:11], vcc, s[0:1]
	v_med3_i32 v93, v60, -15, 15
	v_lshl_add_u32 v253, v93, 2, v91
	ds_read_b32 v243, v253 offset:60
	v_lshl_add_u32 v253, v93, 2, v91
	ds_read_b32 v252, v253 offset:184
	s_waitcnt lgkmcnt(1)
	v_fmac_f32_e32 v243, 0x3db504f3, v61
	v_cndmask_b32_e64 v83, v83, v243, s[10:11]
	v_or_b32_e32 v61, 2, v101
	v_cmp_ge_u32_e32 vcc, v61, v100
	v_cmp_lt_u32_e64 s[0:1], v61, v102
	v_sub_u32_e32 v61, v61, v99
	s_and_b64 s[12:13], vcc, s[0:1]
	v_mov_b32_e32 v60, 0xf149f2ca
	v_med3_i32 v94, v61, -15, 15
	v_mov_b32_e32 v61, 0xf149f2ca
	v_lshl_add_u32 v253, v94, 2, v91
	ds_read_b32 v244, v253 offset:60
	v_lshl_add_u32 v253, v94, 2, v91
	ds_read_b32 v242, v253 offset:184
	s_waitcnt lgkmcnt(1)
	v_fmac_f32_e32 v244, 0x3db504f3, v62
	v_cndmask_b32_e64 v61, v61, v244, s[12:13]
	v_or_b32_e32 v62, 3, v101
	v_cmp_ge_u32_e32 vcc, v62, v100
	v_cmp_lt_u32_e64 s[0:1], v62, v102
	v_sub_u32_e32 v62, v62, v99
	s_and_b64 s[14:15], vcc, s[0:1]
	v_med3_i32 v95, v62, -15, 15
	v_lshl_add_u32 v253, v95, 2, v91
	ds_read_b32 v245, v253 offset:60
	v_lshl_add_u32 v253, v95, 2, v91
	ds_read_b32 v243, v253 offset:184
	s_waitcnt lgkmcnt(1)
	v_fmac_f32_e32 v245, 0x3db504f3, v63
	v_cndmask_b32_e64 v60, v60, v245, s[14:15]
	v_or_b32_e32 v63, 4, v101
	v_cmp_ge_u32_e32 vcc, v63, v100
	v_cmp_lt_u32_e64 s[0:1], v63, v102
	v_sub_u32_e32 v63, v63, v99
	s_and_b64 s[16:17], vcc, s[0:1]
	v_mov_b32_e32 v62, 0xf149f2ca
	v_med3_i32 v96, v63, -15, 15
	v_mov_b32_e32 v63, 0xf149f2ca
	v_lshl_add_u32 v253, v96, 2, v91
	ds_read_b32 v246, v253 offset:60
	v_lshl_add_u32 v253, v96, 2, v91
	ds_read_b32 v244, v253 offset:184
	s_waitcnt lgkmcnt(1)
	v_fmac_f32_e32 v246, 0x3db504f3, v56
	v_cndmask_b32_e64 v63, v63, v246, s[16:17]
	v_or_b32_e32 v56, 5, v101
	v_cmp_ge_u32_e32 vcc, v56, v100
	v_cmp_lt_u32_e64 s[0:1], v56, v102
	v_sub_u32_e32 v56, v56, v99
	s_and_b64 s[18:19], vcc, s[0:1]
	v_med3_i32 v97, v56, -15, 15
	v_lshl_add_u32 v253, v97, 2, v91
	ds_read_b32 v247, v253 offset:60
	v_lshl_add_u32 v253, v97, 2, v91
	ds_read_b32 v245, v253 offset:184
	s_waitcnt lgkmcnt(1)
	v_fmac_f32_e32 v247, 0x3db504f3, v57
	v_cndmask_b32_e64 v62, v62, v247, s[18:19]
	v_or_b32_e32 v57, 6, v101
	v_cmp_ge_u32_e32 vcc, v57, v100
	v_cmp_lt_u32_e64 s[0:1], v57, v102
	v_sub_u32_e32 v57, v57, v99
	s_and_b64 s[20:21], vcc, s[0:1]
	v_mov_b32_e32 v56, 0xf149f2ca
	v_med3_i32 v98, v57, -15, 15
	v_mov_b32_e32 v57, 0xf149f2ca
	v_lshl_add_u32 v253, v98, 2, v91
	ds_read_b32 v249, v253 offset:60
	v_lshl_add_u32 v253, v98, 2, v91
	ds_read_b32 v246, v253 offset:184
	s_waitcnt lgkmcnt(1)
	v_fmac_f32_e32 v249, 0x3db504f3, v58
	v_cndmask_b32_e64 v57, v57, v249, s[20:21]
	v_or_b32_e32 v58, 7, v101
	v_cmp_ge_u32_e32 vcc, v58, v100
	v_cmp_lt_u32_e64 s[0:1], v58, v102
	v_sub_u32_e32 v58, v58, v99
	s_and_b64 s[0:1], vcc, s[0:1]
	v_med3_i32 v99, v58, -15, 15
	v_lshl_add_u32 v253, v99, 2, v91
	ds_read_b32 v250, v253 offset:60
	v_lshl_add_u32 v253, v99, 2, v91
	ds_read_b32 v247, v253 offset:184
	s_waitcnt lgkmcnt(1)
	v_fmac_f32_e32 v250, 0x3db504f3, v59
	v_cndmask_b32_e64 v56, v56, v250, s[0:1]
	v_mov_b32_e32 v58, 0xf149f2ca
	v_mov_b32_e32 v59, 0xf149f2ca
	v_lshl_add_u32 v253, v92, 2, v91
	ds_read_b32 v249, v253 offset:308
	s_waitcnt lgkmcnt(15)
	v_fmac_f32_e32 v251, 0x3db504f3, v52
	v_cndmask_b32_e64 v59, v59, v251, s[8:9]
	v_lshl_add_u32 v253, v93, 2, v91
	ds_read_b32 v250, v253 offset:308
	s_waitcnt lgkmcnt(14)
	v_fmac_f32_e32 v252, 0x3db504f3, v53
	v_cndmask_b32_e64 v58, v58, v252, s[10:11]
	v_mov_b32_e32 v52, 0xf149f2ca
	v_mov_b32_e32 v53, 0xf149f2ca
	v_lshl_add_u32 v253, v94, 2, v91
	ds_read_b32 v251, v253 offset:308
	s_waitcnt lgkmcnt(13)
	v_fmac_f32_e32 v242, 0x3db504f3, v54
	v_cndmask_b32_e64 v53, v53, v242, s[12:13]
	v_lshl_add_u32 v253, v95, 2, v91
	ds_read_b32 v252, v253 offset:308
	s_waitcnt lgkmcnt(12)
	v_fmac_f32_e32 v243, 0x3db504f3, v55
	v_cndmask_b32_e64 v52, v52, v243, s[14:15]
	v_mov_b32_e32 v54, 0xf149f2ca
	v_mov_b32_e32 v55, 0xf149f2ca
	v_lshl_add_u32 v253, v96, 2, v91
	ds_read_b32 v242, v253 offset:308
	s_waitcnt lgkmcnt(11)
	v_fmac_f32_e32 v244, 0x3db504f3, v48
	v_cndmask_b32_e64 v55, v55, v244, s[16:17]
	v_lshl_add_u32 v253, v97, 2, v91
	ds_read_b32 v243, v253 offset:308
	s_waitcnt lgkmcnt(10)
	v_fmac_f32_e32 v245, 0x3db504f3, v49
	v_cndmask_b32_e64 v54, v54, v245, s[18:19]
	v_mov_b32_e32 v48, 0xf149f2ca
	v_mov_b32_e32 v49, 0xf149f2ca
	v_lshl_add_u32 v253, v98, 2, v91
	ds_read_b32 v244, v253 offset:308
	s_waitcnt lgkmcnt(9)
; __device__ void phase_na(const Params& P, unsigned char* smem) {
;     ...
;         for (int i = 0; i < 8; ++i) {
;             const float* brow = rpb_s + (h * 15 + (rs + i - r + 7)) * 31;
; #pragma unroll
;             for (int a = 0; a < 2; ++a)
; #pragma unroll
;                 for (int jj = 0; jj < 4; ++jj) {
;                     const int kc = k0 + l4 * 8 + a * 4 + jj;
;                     const bool valid = (kc >= cs) && (kc < cs + 16);
;                     const int dc = min(max(kc - qc, -15), 15) + 15;
;                     const float s = valid ? st[i][a][jj] * scale + brow[dc] : -1e30f;
;                     st[i][a][jj] = s; mx = fmaxf(mx, s);
;                 }
	v_fmac_f32_e32 v246, 0x3db504f3, v50
	v_cndmask_b32_e64 v49, v49, v246, s[20:21]
	v_lshl_add_u32 v253, v99, 2, v91
	ds_read_b32 v245, v253 offset:308
	s_waitcnt lgkmcnt(8)
	v_fmac_f32_e32 v247, 0x3db504f3, v51
	v_cndmask_b32_e64 v48, v48, v247, s[0:1]
	v_mov_b32_e32 v50, 0xf149f2ca
	v_mov_b32_e32 v51, 0xf149f2ca
	v_lshl_add_u32 v253, v92, 2, v91
	ds_read_b32 v246, v253 offset:432
	s_waitcnt lgkmcnt(8)
	v_fmac_f32_e32 v249, 0x3db504f3, v44
	v_cndmask_b32_e64 v51, v51, v249, s[8:9]
	v_lshl_add_u32 v253, v93, 2, v91
	ds_read_b32 v247, v253 offset:432
	s_waitcnt lgkmcnt(8)
	v_fmac_f32_e32 v250, 0x3db504f3, v45
	v_cndmask_b32_e64 v50, v50, v250, s[10:11]
	v_mov_b32_e32 v44, 0xf149f2ca
	v_mov_b32_e32 v45, 0xf149f2ca
	v_lshl_add_u32 v253, v94, 2, v91
	ds_read_b32 v249, v253 offset:432
	s_waitcnt lgkmcnt(8)
	v_fmac_f32_e32 v251, 0x3db504f3, v46
	v_cndmask_b32_e64 v45, v45, v251, s[12:13]
	v_lshl_add_u32 v253, v95, 2, v91
	ds_read_b32 v250, v253 offset:432
	s_waitcnt lgkmcnt(8)
	v_fmac_f32_e32 v252, 0x3db504f3, v47
	v_cndmask_b32_e64 v44, v44, v252, s[14:15]
	v_mov_b32_e32 v46, 0xf149f2ca
	v_mov_b32_e32 v47, 0xf149f2ca
	v_lshl_add_u32 v253, v96, 2, v91
	ds_read_b32 v251, v253 offset:432
	s_waitcnt lgkmcnt(8)
	v_fmac_f32_e32 v242, 0x3db504f3, v40
	v_cndmask_b32_e64 v47, v47, v242, s[16:17]
	v_lshl_add_u32 v253, v97, 2, v91
	ds_read_b32 v252, v253 offset:432
	s_waitcnt lgkmcnt(8)
	v_fmac_f32_e32 v243, 0x3db504f3, v41
	v_cndmask_b32_e64 v46, v46, v243, s[18:19]
	v_mov_b32_e32 v40, 0xf149f2ca
	v_mov_b32_e32 v41, 0xf149f2ca
	v_lshl_add_u32 v253, v98, 2, v91
	ds_read_b32 v242, v253 offset:432
	s_waitcnt lgkmcnt(8)
	v_fmac_f32_e32 v244, 0x3db504f3, v42
	v_cndmask_b32_e64 v41, v41, v244, s[20:21]
	v_lshl_add_u32 v253, v99, 2, v91
	ds_read_b32 v243, v253 offset:432
	s_waitcnt lgkmcnt(8)
	v_fmac_f32_e32 v245, 0x3db504f3, v43
	v_cndmask_b32_e64 v40, v40, v245, s[0:1]
	v_mov_b32_e32 v42, 0xf149f2ca
	v_mov_b32_e32 v43, 0xf149f2ca
	v_lshl_add_u32 v253, v92, 2, v91
	ds_read_b32 v244, v253 offset:556
	s_waitcnt lgkmcnt(8)
	v_fmac_f32_e32 v246, 0x3db504f3, v36
	v_cndmask_b32_e64 v43, v43, v246, s[8:9]
	v_lshl_add_u32 v253, v93, 2, v91
	ds_read_b32 v245, v253 offset:556
	s_waitcnt lgkmcnt(8)
	v_fmac_f32_e32 v247, 0x3db504f3, v37
	v_cndmask_b32_e64 v42, v42, v247, s[10:11]
	v_mov_b32_e32 v100, 0xf149f2ca
	v_mov_b32_e32 v102, 0xf149f2ca
	v_lshl_add_u32 v253, v94, 2, v91
	ds_read_b32 v246, v253 offset:556
	s_waitcnt lgkmcnt(8)
	v_fmac_f32_e32 v249, 0x3db504f3, v38
	v_cndmask_b32_e64 v102, v102, v249, s[12:13]
	v_lshl_add_u32 v253, v95, 2, v91
	ds_read_b32 v247, v253 offset:556
	s_waitcnt lgkmcnt(8)
	v_fmac_f32_e32 v250, 0x3db504f3, v39
	v_cndmask_b32_e64 v100, v100, v250, s[14:15]
	v_mov_b32_e32 v36, 0xf149f2ca
	v_mov_b32_e32 v37, 0xf149f2ca
	v_lshl_add_u32 v253, v96, 2, v91
	ds_read_b32 v249, v253 offset:556
	s_waitcnt lgkmcnt(8)
	v_fmac_f32_e32 v251, 0x3db504f3, v32
	v_cndmask_b32_e64 v37, v37, v251, s[16:17]
	v_lshl_add_u32 v253, v97, 2, v91
	ds_read_b32 v250, v253 offset:556
	s_waitcnt lgkmcnt(8)
	v_fmac_f32_e32 v252, 0x3db504f3, v33
	v_cndmask_b32_e64 v36, v36, v252, s[18:19]
	v_mov_b32_e32 v32, 0xf149f2ca
	v_mov_b32_e32 v33, 0xf149f2ca
	v_lshl_add_u32 v253, v98, 2, v91
	ds_read_b32 v251, v253 offset:556
	s_waitcnt lgkmcnt(8)
	v_fmac_f32_e32 v242, 0x3db504f3, v34
	v_cndmask_b32_e64 v33, v33, v242, s[20:21]
	v_lshl_add_u32 v253, v99, 2, v91
	ds_read_b32 v252, v253 offset:556
	s_waitcnt lgkmcnt(8)
	v_fmac_f32_e32 v243, 0x3db504f3, v35
	v_cndmask_b32_e64 v32, v32, v243, s[0:1]
	v_mov_b32_e32 v34, 0xf149f2ca
	v_mov_b32_e32 v35, 0xf149f2ca
	v_lshl_add_u32 v253, v92, 2, v91
	ds_read_b32 v242, v253 offset:680
	s_waitcnt lgkmcnt(8)
	v_fmac_f32_e32 v244, 0x3db504f3, v28
	v_cndmask_b32_e64 v35, v35, v244, s[8:9]
	v_lshl_add_u32 v253, v93, 2, v91
	ds_read_b32 v243, v253 offset:680
	s_waitcnt lgkmcnt(8)
	v_fmac_f32_e32 v245, 0x3db504f3, v29
	v_cndmask_b32_e64 v34, v34, v245, s[10:11]
	v_mov_b32_e32 v28, 0xf149f2ca
	v_mov_b32_e32 v29, 0xf149f2ca
	v_lshl_add_u32 v253, v94, 2, v91
	ds_read_b32 v244, v253 offset:680
	s_waitcnt lgkmcnt(8)
	v_fmac_f32_e32 v246, 0x3db504f3, v30
	v_cndmask_b32_e64 v29, v29, v246, s[12:13]
	v_lshl_add_u32 v253, v95, 2, v91
	ds_read_b32 v245, v253 offset:680
	s_waitcnt lgkmcnt(8)
	v_fmac_f32_e32 v247, 0x3db504f3, v31
	v_cndmask_b32_e64 v28, v28, v247, s[14:15]
	v_mov_b32_e32 v30, 0xf149f2ca
	v_mov_b32_e32 v31, 0xf149f2ca
	v_lshl_add_u32 v253, v96, 2, v91
	ds_read_b32 v246, v253 offset:680
	s_waitcnt lgkmcnt(8)
	v_fmac_f32_e32 v249, 0x3db504f3, v24
	v_cndmask_b32_e64 v31, v31, v249, s[16:17]
	v_lshl_add_u32 v253, v97, 2, v91
	ds_read_b32 v247, v253 offset:680
	s_waitcnt lgkmcnt(8)
; __device__ void phase_na(const Params& P, unsigned char* smem) {
;     ...
;         for (int i = 0; i < 8; ++i) {
;             const float* brow = rpb_s + (h * 15 + (rs + i - r + 7)) * 31;
; #pragma unroll
;             for (int a = 0; a < 2; ++a)
; #pragma unroll
;                 for (int jj = 0; jj < 4; ++jj) {
;                     const int kc = k0 + l4 * 8 + a * 4 + jj;
;                     const bool valid = (kc >= cs) && (kc < cs + 16);
;                     const int dc = min(max(kc - qc, -15), 15) + 15;
;                     const float s = valid ? st[i][a][jj] * scale + brow[dc] : -1e30f;
;                     st[i][a][jj] = s; mx = fmaxf(mx, s);
;                 }
	v_fmac_f32_e32 v250, 0x3db504f3, v25
	v_cndmask_b32_e64 v30, v30, v250, s[18:19]
	v_mov_b32_e32 v24, 0xf149f2ca
	v_mov_b32_e32 v25, 0xf149f2ca
	v_lshl_add_u32 v253, v98, 2, v91
	ds_read_b32 v249, v253 offset:680
	s_waitcnt lgkmcnt(8)
	v_fmac_f32_e32 v251, 0x3db504f3, v26
	v_cndmask_b32_e64 v25, v25, v251, s[20:21]
	v_lshl_add_u32 v253, v99, 2, v91
	ds_read_b32 v250, v253 offset:680
	s_waitcnt lgkmcnt(8)
	v_fmac_f32_e32 v252, 0x3db504f3, v27
	v_cndmask_b32_e64 v24, v24, v252, s[0:1]
	v_mov_b32_e32 v26, 0xf149f2ca
	v_mov_b32_e32 v27, 0xf149f2ca
	v_lshl_add_u32 v253, v92, 2, v91
	ds_read_b32 v251, v253 offset:804
	s_waitcnt lgkmcnt(8)
	v_fmac_f32_e32 v242, 0x3db504f3, v20
	v_cndmask_b32_e64 v27, v27, v242, s[8:9]
	v_lshl_add_u32 v253, v93, 2, v91
	ds_read_b32 v252, v253 offset:804
	s_waitcnt lgkmcnt(8)
	v_fmac_f32_e32 v243, 0x3db504f3, v21
	v_cndmask_b32_e64 v26, v26, v243, s[10:11]
	v_mov_b32_e32 v20, 0xf149f2ca
	v_mov_b32_e32 v38, 0xf149f2ca
	v_lshl_add_u32 v253, v94, 2, v91
	ds_read_b32 v242, v253 offset:804
	s_waitcnt lgkmcnt(8)
	v_fmac_f32_e32 v244, 0x3db504f3, v22
	v_cndmask_b32_e64 v38, v38, v244, s[12:13]
	v_lshl_add_u32 v253, v95, 2, v91
	ds_read_b32 v243, v253 offset:804
	s_waitcnt lgkmcnt(8)
	v_fmac_f32_e32 v245, 0x3db504f3, v23
	v_cndmask_b32_e64 v20, v20, v245, s[14:15]
	v_mov_b32_e32 v21, 0xf149f2ca
	v_mov_b32_e32 v22, 0xf149f2ca
	v_lshl_add_u32 v253, v96, 2, v91
	ds_read_b32 v244, v253 offset:804
	s_waitcnt lgkmcnt(8)
	v_fmac_f32_e32 v246, 0x3db504f3, v16
	v_cndmask_b32_e64 v22, v22, v246, s[16:17]
	v_lshl_add_u32 v253, v97, 2, v91
	ds_read_b32 v245, v253 offset:804
	s_waitcnt lgkmcnt(8)
	v_fmac_f32_e32 v247, 0x3db504f3, v17
	v_cndmask_b32_e64 v21, v21, v247, s[18:19]
	v_mov_b32_e32 v16, 0xf149f2ca
	v_mov_b32_e32 v23, 0xf149f2ca
	v_lshl_add_u32 v253, v98, 2, v91
	ds_read_b32 v246, v253 offset:804
	s_waitcnt lgkmcnt(8)
	v_fmac_f32_e32 v249, 0x3db504f3, v18
	v_cndmask_b32_e64 v23, v23, v249, s[20:21]
	v_lshl_add_u32 v253, v99, 2, v91
	ds_read_b32 v247, v253 offset:804
	s_waitcnt lgkmcnt(8)
	v_fmac_f32_e32 v250, 0x3db504f3, v19
	v_cndmask_b32_e64 v16, v16, v250, s[0:1]
	v_mov_b32_e32 v17, 0xf149f2ca
	v_mov_b32_e32 v19, 0xf149f2ca
	v_lshl_add_u32 v253, v92, 2, v91
	ds_read_b32 v249, v253 offset:928
	s_waitcnt lgkmcnt(8)
	v_fmac_f32_e32 v251, 0x3db504f3, v12
	v_cndmask_b32_e64 v19, v19, v251, s[8:9]
	v_lshl_add_u32 v253, v93, 2, v91
	ds_read_b32 v250, v253 offset:928
	s_waitcnt lgkmcnt(8)
	v_fmac_f32_e32 v252, 0x3db504f3, v13
	v_cndmask_b32_e64 v17, v17, v252, s[10:11]
	v_mov_b32_e32 v18, 0xf149f2ca
	v_mov_b32_e32 v39, 0xf149f2ca
	v_lshl_add_u32 v253, v94, 2, v91
	ds_read_b32 v251, v253 offset:928
	s_waitcnt lgkmcnt(8)
	v_fmac_f32_e32 v242, 0x3db504f3, v14
	v_cndmask_b32_e64 v39, v39, v242, s[12:13]
	v_lshl_add_u32 v253, v95, 2, v91
	ds_read_b32 v252, v253 offset:928
	s_waitcnt lgkmcnt(8)
	v_fmac_f32_e32 v243, 0x3db504f3, v15
	v_cndmask_b32_e64 v18, v18, v243, s[14:15]
	v_mov_b32_e32 v101, 0xf149f2ca
	v_mov_b32_e32 v103, 0xf149f2ca
	v_lshl_add_u32 v253, v96, 2, v91
	ds_read_b32 v242, v253 offset:928
	s_waitcnt lgkmcnt(8)
	v_fmac_f32_e32 v244, 0x3db504f3, v8
	v_cndmask_b32_e64 v103, v103, v244, s[16:17]
	v_lshl_add_u32 v253, v97, 2, v91
	ds_read_b32 v243, v253 offset:928
	s_waitcnt lgkmcnt(8)
	v_fmac_f32_e32 v245, 0x3db504f3, v9
	v_cndmask_b32_e64 v101, v101, v245, s[18:19]
	v_mov_b32_e32 v104, 0xf149f2ca
	v_mov_b32_e32 v106, 0xf149f2ca
	v_lshl_add_u32 v253, v98, 2, v91
	ds_read_b32 v244, v253 offset:928
	s_waitcnt lgkmcnt(8)
	v_fmac_f32_e32 v246, 0x3db504f3, v10
	v_cndmask_b32_e64 v106, v106, v246, s[20:21]
	s_waitcnt lgkmcnt(7)
	v_fmac_f32_e32 v247, 0x3db504f3, v11
	v_cndmask_b32_e64 v104, v104, v247, s[0:1]
	v_mov_b32_e32 v105, 0xf149f2ca
	v_mov_b32_e32 v107, 0xf149f2ca
	s_waitcnt lgkmcnt(6)
	v_fmac_f32_e32 v249, 0x3db504f3, v4
	v_cndmask_b32_e64 v107, v107, v249, s[8:9]
	s_waitcnt lgkmcnt(5)
	v_fmac_f32_e32 v250, 0x3db504f3, v5
	v_cndmask_b32_e64 v105, v105, v250, s[10:11]
	v_mov_b32_e32 v92, 0xf149f2ca
	v_mov_b32_e32 v108, 0xf149f2ca
	s_waitcnt lgkmcnt(4)
	v_fmac_f32_e32 v251, 0x3db504f3, v6
	v_cndmask_b32_e64 v108, v108, v251, s[12:13]
	s_waitcnt lgkmcnt(3)
	v_fmac_f32_e32 v252, 0x3db504f3, v7
	v_cndmask_b32_e64 v92, v92, v252, s[14:15]
	v_mov_b32_e32 v93, 0xf149f2ca
	v_mov_b32_e32 v94, 0xf149f2ca
	s_waitcnt lgkmcnt(2)
	v_fmac_f32_e32 v242, 0x3db504f3, v0
	v_cndmask_b32_e64 v94, v94, v242, s[16:17]
	s_waitcnt lgkmcnt(1)
	v_fmac_f32_e32 v243, 0x3db504f3, v1
	v_cndmask_b32_e64 v93, v93, v243, s[18:19]
	v_mov_b32_e32 v95, 0xf149f2ca
	v_mov_b32_e32 v96, 0xf149f2ca
	s_waitcnt lgkmcnt(0)
	v_fmac_f32_e32 v244, 0x3db504f3, v2
	v_cndmask_b32_e64 v96, v96, v244, s[20:21]
	s_and_saveexec_b64 s[8:9], s[0:1]
	s_cbranch_execz .LBB0_209
	v_lshl_add_u32 v0, v99, 2, v91
	ds_read_b32 v95, v0 offset:928
	s_waitcnt lgkmcnt(0)
	v_fmac_f32_e32 v95, 0x3db504f3, v3
	s_branch .LBB0_209

; __global__ __launch_bounds__(512, 2) void mega(Params P) {
;     extern __shared__ __attribute__((aligned(16))) unsigned char shm[];
	.amdhsa_kernel _Z4mega6Params
		.amdhsa_group_segment_fixed_size 0
		.amdhsa_private_segment_fixed_size 0
		.amdhsa_kernarg_size 488
		.amdhsa_user_sgpr_count 2
		.amdhsa_user_sgpr_dispatch_ptr 0
		.amdhsa_user_sgpr_queue_ptr 0
		.amdhsa_user_sgpr_kernarg_segment_ptr 1
		.amdhsa_user_sgpr_dispatch_id 0
		.amdhsa_user_sgpr_kernarg_preload_length 0
		.amdhsa_user_sgpr_kernarg_preload_offset 0
		.amdhsa_user_sgpr_private_segment_size 0
		.amdhsa_uses_dynamic_stack 0
		.amdhsa_enable_private_segment 0
		.amdhsa_system_sgpr_workgroup_id_x 1
		.amdhsa_system_sgpr_workgroup_id_y 0
		.amdhsa_system_sgpr_workgroup_id_z 0
		.amdhsa_system_sgpr_workgroup_info 0
		.amdhsa_system_vgpr_workitem_id 2
		.amdhsa_next_free_vgpr 256
		.amdhsa_next_free_sgpr 98
		.amdhsa_accum_offset 256
		.amdhsa_reserve_vcc 1
		.amdhsa_float_round_mode_32 0
		.amdhsa_float_round_mode_16_64 0
		.amdhsa_float_denorm_mode_32 3
		.amdhsa_float_denorm_mode_16_64 3
		.amdhsa_dx10_clamp 1
		.amdhsa_ieee_mode 1
		.amdhsa_fp16_overflow 0
		.amdhsa_tg_split 0
		.amdhsa_exception_fp_ieee_invalid_op 0
		.amdhsa_exception_fp_denorm_src 0
		.amdhsa_exception_fp_ieee_div_zero 0
		.amdhsa_exception_fp_ieee_overflow 0
		.amdhsa_exception_fp_ieee_underflow 0
		.amdhsa_exception_fp_ieee_inexact 0
		.amdhsa_exception_int_div_zero 0
	.end_amdhsa_kernel

; __global__ __launch_bounds__(512, 2) void mega(Params P) {
;     extern __shared__ __attribute__((aligned(16))) unsigned char shm[];
amdhsa.kernels:
  - .agpr_count:     0
    .args:
      - .offset:         0
        .size:           232
        .value_kind:     by_value
      - .offset:         232
        .size:           4
        .value_kind:     hidden_block_count_x
      - .offset:         236
        .size:           4
        .value_kind:     hidden_block_count_y
      - .offset:         240
        .size:           4
        .value_kind:     hidden_block_count_z
      - .offset:         244
        .size:           2
        .value_kind:     hidden_group_size_x
      - .offset:         246
        .size:           2
        .value_kind:     hidden_group_size_y
      - .offset:         248
        .size:           2
        .value_kind:     hidden_group_size_z
      - .offset:         250
        .size:           2
        .value_kind:     hidden_remainder_x
      - .offset:         252
        .size:           2
        .value_kind:     hidden_remainder_y
      - .offset:         254
        .size:           2
        .value_kind:     hidden_remainder_z
      - .offset:         272
        .size:           8
        .value_kind:     hidden_global_offset_x
      - .offset:         280
        .size:           8
        .value_kind:     hidden_global_offset_y
      - .offset:         288
        .size:           8
        .value_kind:     hidden_global_offset_z
      - .offset:         296
        .size:           2
        .value_kind:     hidden_grid_dims
      - .offset:         320
        .size:           8
        .value_kind:     hidden_multigrid_sync_arg
      - .offset:         352
        .size:           4
        .value_kind:     hidden_dynamic_lds_size
    .group_segment_fixed_size: 0
    .kernarg_segment_align: 8
    .kernarg_segment_size: 488
    .language:       OpenCL C
    .language_version:
      - 2
      - 0
    .max_flat_workgroup_size: 512
    .name:           _Z4mega6Params
    .private_segment_fixed_size: 0
    .sgpr_count:     104
    .sgpr_spill_count: 38
    .symbol:         _Z4mega6Params.kd
    .uniform_work_group_size: 1
    .uses_dynamic_stack: false
    .vgpr_count:     256
    .vgpr_spill_count: 0
    .wavefront_size: 64
